# grid barrier: all waiters (leaders and non-leaders) poll the top-level arrival counter against (generation+1)*nXCD; the generation-word hop is off the critical path
# speedup vs baseline: 1.0111x; 1.0004x over previous
; __device__ __forceinline__ unsigned xb_ld(unsigned* p)              { return __hip_atomic_load(p, __ATOMIC_RELAXED, __HIP_MEMORY_SCOPE_AGENT); }
; __device__ __forceinline__ unsigned xb_add(unsigned* p, unsigned v) { return __hip_atomic_fetch_add(p, v, __ATOMIC_RELAXED, __HIP_MEMORY_SCOPE_AGENT); }
; #define XB_SPIN(cond, bar) do { unsigned _sp = 0; while (cond) { __builtin_amdgcn_s_sleep(1); \
;     if ((++_sp & 255u) == 0u) { if (xb_ld(&(bar)[XB_TMO])) break; if (_sp > XB_SPIN_CAP) { atomicAdd(&(bar)[XB_TMO], 1u); break; } } } } while (0)
; __device__ __forceinline__ void xcd_barrier(const XcdBarrier& b) {
;     ...
;         const unsigned old = xb_add(&bar[XB_XSUB(b.x)], 1u);
;         const unsigned gen = old / nloc;
;         if (old + 1u == (gen + 1u) * nloc) {
;             __builtin_amdgcn_fence(__ATOMIC_RELEASE, "agent");
;             asm volatile("s_waitcnt vmcnt(0)" ::: "memory");
;             const unsigned og = xb_add(&bar[XB_TOP], 1u);
;             const unsigned tg = og / nx;
;             if (og + 1u == (tg + 1u) * nx) xb_add(&bar[XB_TOPGEN], 1u);
;             else XB_SPIN(xb_ld(&bar[XB_TOPGEN]) == tg, bar);
;             __builtin_amdgcn_fence(__ATOMIC_ACQUIRE, "agent");
;             xb_add(&bar[XB_XGEN(b.x)], 1u);
;             asm volatile("s_waitcnt vmcnt(0)" ::: "memory");
;         } else {
;             XB_SPIN(xb_ld(&bar[XB_XGEN(b.x)]) == gen, bar);
.LBB0_77:
	s_or_b64 exec, exec, s[8:9]
	v_cvt_f32_u32_e32 v4, v2
	s_waitcnt vmcnt(0)
	v_readfirstlane_b32 s6, v3
	v_sub_u32_e32 v3, 0, v2
	v_rcp_iflag_f32_e32 v4, v4
	v_add_u32_e32 v5, s6, v1
	v_mul_f32_e32 v4, 0x4f7ffffe, v4
	v_cvt_u32_f32_e32 v4, v4
	v_mul_lo_u32 v1, v3, v4
	v_mul_hi_u32 v1, v4, v1
	v_add_u32_e32 v1, v4, v1
	v_mul_hi_u32 v1, v5, v1
	v_mul_lo_u32 v3, v1, v2
	v_sub_u32_e32 v3, v5, v3
	v_add_u32_e32 v4, 1, v1
	v_cmp_ge_u32_e32 vcc, v3, v2
	s_nop 1
	v_cndmask_b32_e32 v1, v1, v4, vcc
	v_sub_u32_e32 v4, v3, v2
	v_cndmask_b32_e32 v3, v3, v4, vcc
	v_add_u32_e32 v4, 1, v1
	v_cmp_ge_u32_e32 vcc, v3, v2
	v_add_u32_e32 v3, 1, v5
	s_nop 0
	v_cndmask_b32_e32 v1, v1, v4, vcc
	v_mul_lo_u32 v4, v2, v1
	v_add_u32_e32 v2, v4, v2
	v_cmp_ne_u32_e32 vcc, v3, v2
	s_and_saveexec_b64 s[6:7], vcc
	s_xor_b64 s[6:7], exec, s[6:7]
	s_cbranch_execz .LBB0_91
	s_waitcnt lgkmcnt(0)
	s_add_u32 s34, s94, 0x43400
	s_addc_u32 s35, s95, 0
	v_mad_u32_u24 v1, v1, v0, v0
	v_mov_b32_e32 v0, 0
	global_load_dword v0, v0, s[34:35] sc1
	s_waitcnt vmcnt(0)
	v_cmp_lt_u32_e32 vcc, v0, v1
	s_and_saveexec_b64 s[8:9], vcc
	s_cbranch_execz .LBB0_90
	s_add_u32 s10, s94, 0x40200
	s_addc_u32 s11, s95, 0
	s_mov_b32 s18, 1
	s_mov_b64 s[36:37], 0
	v_mov_b32_e32 v0, 0
	s_branch .LBB0_81

; __device__ __forceinline__ unsigned xb_ld(unsigned* p)              { return __hip_atomic_load(p, __ATOMIC_RELAXED, __HIP_MEMORY_SCOPE_AGENT); }
; #define XB_SPIN(cond, bar) do { unsigned _sp = 0; while (cond) { __builtin_amdgcn_s_sleep(1); \
;     if ((++_sp & 255u) == 0u) { if (xb_ld(&(bar)[XB_TMO])) break; if (_sp > XB_SPIN_CAP) { atomicAdd(&(bar)[XB_TMO], 1u); break; } } } } while (0)
; __device__ __forceinline__ void xcd_barrier(const XcdBarrier& b) {
;     ...
;             XB_SPIN(xb_ld(&bar[XB_XGEN(b.x)]) == gen, bar);
.LBB0_83:
	global_load_dword v2, v0, s[34:35] sc1
	s_add_i32 s18, s18, 1
	s_mov_b64 s[14:15], -1
	s_waitcnt vmcnt(0)
	v_cmp_ge_u32_e32 vcc, v2, v1
	s_orn2_b64 s[12:13], vcc, exec
	s_branch .LBB0_80

; __device__ __forceinline__ unsigned xb_ld(unsigned* p)              { return __hip_atomic_load(p, __ATOMIC_RELAXED, __HIP_MEMORY_SCOPE_AGENT); }
; __device__ __forceinline__ unsigned xb_add(unsigned* p, unsigned v) { return __hip_atomic_fetch_add(p, v, __ATOMIC_RELAXED, __HIP_MEMORY_SCOPE_AGENT); }
; #define XB_SPIN(cond, bar) do { unsigned _sp = 0; while (cond) { __builtin_amdgcn_s_sleep(1); \
;     if ((++_sp & 255u) == 0u) { if (xb_ld(&(bar)[XB_TMO])) break; if (_sp > XB_SPIN_CAP) { atomicAdd(&(bar)[XB_TMO], 1u); break; } } } } while (0)
; __device__ __forceinline__ void xcd_barrier(const XcdBarrier& b) {
;     ...
;             const unsigned og = xb_add(&bar[XB_TOP], 1u);
;             const unsigned tg = og / nx;
;             if (og + 1u == (tg + 1u) * nx) xb_add(&bar[XB_TOPGEN], 1u);
;             else XB_SPIN(xb_ld(&bar[XB_TOPGEN]) == tg, bar);
.LBB0_94:
	s_or_b64 exec, exec, s[8:9]
	v_cvt_f32_u32_e32 v3, v0
	s_waitcnt vmcnt(0)
	v_readfirstlane_b32 s6, v2
	s_add_u32 s8, s94, 0x43500
	s_addc_u32 s9, s95, 0
	v_rcp_iflag_f32_e32 v3, v3
	v_add_u32_e32 v1, s6, v1
	v_add_u32_e32 v4, 1, v1
	s_mov_b64 s[10:11], -1
	v_mul_f32_e32 v2, 0x4f7ffffe, v3
	v_cvt_u32_f32_e32 v2, v2
	v_sub_u32_e32 v3, 0, v0
	v_mul_lo_u32 v3, v3, v2
	v_mul_hi_u32 v3, v2, v3
	v_add_u32_e32 v2, v2, v3
	v_mul_hi_u32 v2, v1, v2
	v_mul_lo_u32 v3, v2, v0
	v_sub_u32_e32 v1, v1, v3
	v_add_u32_e32 v5, 1, v2
	v_cmp_ge_u32_e32 vcc, v1, v0
	v_sub_u32_e32 v3, v1, v0
	s_nop 0
	v_cndmask_b32_e32 v2, v2, v5, vcc
	v_cndmask_b32_e32 v1, v1, v3, vcc
	v_add_u32_e32 v3, 1, v2
	v_cmp_ge_u32_e32 vcc, v1, v0
	s_nop 1
	v_cndmask_b32_e32 v2, v2, v3, vcc
	v_mul_lo_u32 v1, v0, v2
	v_add_u32_e32 v0, v1, v0
	v_mov_b32_e32 v30, v0
	v_cmp_ne_u32_e32 vcc, v4, v0
	v_mov_b64_e32 v[0:1], s[8:9]
	s_and_saveexec_b64 s[6:7], vcc
	s_cbranch_execz .LBB0_106
	v_mov_b32_e32 v0, 0
	global_load_dword v1, v0, s[8:9] offset:-256 sc1
	s_mov_b64 s[12:13], 0
	s_waitcnt vmcnt(0)
	v_cmp_lt_u32_e32 vcc, v1, v30
	s_and_saveexec_b64 s[34:35], vcc
	s_cbranch_execz .LBB0_105
	s_add_u32 s10, s94, 0x40200
	s_addc_u32 s11, s95, 0
	s_mov_b32 s18, 1
	s_mov_b64 s[36:37], 0
	s_branch .LBB0_98

; __device__ __forceinline__ unsigned xb_ld(unsigned* p)              { return __hip_atomic_load(p, __ATOMIC_RELAXED, __HIP_MEMORY_SCOPE_AGENT); }
; #define XB_SPIN(cond, bar) do { unsigned _sp = 0; while (cond) { __builtin_amdgcn_s_sleep(1); \
;     if ((++_sp & 255u) == 0u) { if (xb_ld(&(bar)[XB_TMO])) break; if (_sp > XB_SPIN_CAP) { atomicAdd(&(bar)[XB_TMO], 1u); break; } } } } while (0)
; __device__ __forceinline__ void xcd_barrier(const XcdBarrier& b) {
;     ...
;             else XB_SPIN(xb_ld(&bar[XB_TOPGEN]) == tg, bar);
.LBB0_100:
	global_load_dword v1, v0, s[8:9] offset:-256 sc1
	s_add_i32 s18, s18, 1
	s_mov_b64 s[12:13], -1
	s_waitcnt vmcnt(0)
	v_cmp_ge_u32_e32 vcc, v1, v30
	s_orn2_b64 s[44:45], vcc, exec
	s_branch .LBB0_97

; __device__ __forceinline__ unsigned xb_ld(unsigned* p)              { return __hip_atomic_load(p, __ATOMIC_RELAXED, __HIP_MEMORY_SCOPE_AGENT); }
; __device__ __forceinline__ unsigned xb_add(unsigned* p, unsigned v) { return __hip_atomic_fetch_add(p, v, __ATOMIC_RELAXED, __HIP_MEMORY_SCOPE_AGENT); }
; #define XB_SPIN(cond, bar) do { unsigned _sp = 0; while (cond) { __builtin_amdgcn_s_sleep(1); \
;     if ((++_sp & 255u) == 0u) { if (xb_ld(&(bar)[XB_TMO])) break; if (_sp > XB_SPIN_CAP) { atomicAdd(&(bar)[XB_TMO], 1u); break; } } } } while (0)
; __device__ __forceinline__ void xcd_barrier(const XcdBarrier& b) {
;     ...
;         const unsigned old = xb_add(&bar[XB_XSUB(b.x)], 1u);
;         const unsigned gen = old / nloc;
;         if (old + 1u == (gen + 1u) * nloc) {
;             __builtin_amdgcn_fence(__ATOMIC_RELEASE, "agent");
;             asm volatile("s_waitcnt vmcnt(0)" ::: "memory");
;             const unsigned og = xb_add(&bar[XB_TOP], 1u);
;             const unsigned tg = og / nx;
;             if (og + 1u == (tg + 1u) * nx) xb_add(&bar[XB_TOPGEN], 1u);
;             else XB_SPIN(xb_ld(&bar[XB_TOPGEN]) == tg, bar);
;             __builtin_amdgcn_fence(__ATOMIC_ACQUIRE, "agent");
;             xb_add(&bar[XB_XGEN(b.x)], 1u);
;             asm volatile("s_waitcnt vmcnt(0)" ::: "memory");
;         } else {
;             XB_SPIN(xb_ld(&bar[XB_XGEN(b.x)]) == gen, bar);
.LBB0_360:
	s_or_b64 exec, exec, s[8:9]
	v_cvt_f32_u32_e32 v4, v2
	s_waitcnt vmcnt(0)
	v_readfirstlane_b32 s6, v3
	v_sub_u32_e32 v3, 0, v2
	v_rcp_iflag_f32_e32 v4, v4
	v_add_u32_e32 v5, s6, v1
	v_mul_f32_e32 v4, 0x4f7ffffe, v4
	v_cvt_u32_f32_e32 v4, v4
	v_mul_lo_u32 v1, v3, v4
	v_mul_hi_u32 v1, v4, v1
	v_add_u32_e32 v1, v4, v1
	v_mul_hi_u32 v1, v5, v1
	v_mul_lo_u32 v3, v1, v2
	v_sub_u32_e32 v3, v5, v3
	v_add_u32_e32 v4, 1, v1
	v_cmp_ge_u32_e32 vcc, v3, v2
	s_nop 1
	v_cndmask_b32_e32 v1, v1, v4, vcc
	v_sub_u32_e32 v4, v3, v2
	v_cndmask_b32_e32 v3, v3, v4, vcc
	v_add_u32_e32 v4, 1, v1
	v_cmp_ge_u32_e32 vcc, v3, v2
	v_add_u32_e32 v3, 1, v5
	s_nop 0
	v_cndmask_b32_e32 v1, v1, v4, vcc
	v_mul_lo_u32 v4, v2, v1
	v_add_u32_e32 v2, v4, v2
	v_cmp_ne_u32_e32 vcc, v3, v2
	s_and_saveexec_b64 s[6:7], vcc
	s_xor_b64 s[6:7], exec, s[6:7]
	s_cbranch_execz .LBB0_374
	s_waitcnt lgkmcnt(0)
	s_add_u32 s34, s94, 0x43400
	s_addc_u32 s35, s95, 0
	v_mad_u32_u24 v1, v1, v0, v0
	v_mov_b32_e32 v0, 0
	global_load_dword v0, v0, s[34:35] sc1
	s_waitcnt vmcnt(0)
	v_cmp_lt_u32_e32 vcc, v0, v1
	s_and_saveexec_b64 s[8:9], vcc
	s_cbranch_execz .LBB0_373
	s_add_u32 s10, s94, 0x40200
	s_addc_u32 s11, s95, 0
	s_mov_b32 s18, 1
	s_mov_b64 s[48:49], 0
	v_mov_b32_e32 v0, 0
	s_branch .LBB0_364

; __device__ __forceinline__ unsigned xb_ld(unsigned* p)              { return __hip_atomic_load(p, __ATOMIC_RELAXED, __HIP_MEMORY_SCOPE_AGENT); }
; __device__ __forceinline__ unsigned xb_add(unsigned* p, unsigned v) { return __hip_atomic_fetch_add(p, v, __ATOMIC_RELAXED, __HIP_MEMORY_SCOPE_AGENT); }
; #define XB_SPIN(cond, bar) do { unsigned _sp = 0; while (cond) { __builtin_amdgcn_s_sleep(1); \
;     if ((++_sp & 255u) == 0u) { if (xb_ld(&(bar)[XB_TMO])) break; if (_sp > XB_SPIN_CAP) { atomicAdd(&(bar)[XB_TMO], 1u); break; } } } } while (0)
; __device__ __forceinline__ void xcd_barrier(const XcdBarrier& b) {
;     ...
;             const unsigned og = xb_add(&bar[XB_TOP], 1u);
;             const unsigned tg = og / nx;
;             if (og + 1u == (tg + 1u) * nx) xb_add(&bar[XB_TOPGEN], 1u);
;             else XB_SPIN(xb_ld(&bar[XB_TOPGEN]) == tg, bar);
.LBB0_377:
	s_or_b64 exec, exec, s[10:11]
	v_cvt_f32_u32_e32 v3, v0
	s_waitcnt vmcnt(0)
	v_readfirstlane_b32 s8, v2
	s_add_u32 s10, s94, 0x43500
	s_addc_u32 s11, s95, 0
	v_rcp_iflag_f32_e32 v3, v3
	v_add_u32_e32 v1, s8, v1
	v_add_u32_e32 v4, 1, v1
	s_mov_b64 s[12:13], -1
	v_mul_f32_e32 v2, 0x4f7ffffe, v3
	v_cvt_u32_f32_e32 v2, v2
	v_sub_u32_e32 v3, 0, v0
	v_mul_lo_u32 v3, v3, v2
	v_mul_hi_u32 v3, v2, v3
	v_add_u32_e32 v2, v2, v3
	v_mul_hi_u32 v2, v1, v2
	v_mul_lo_u32 v3, v2, v0
	v_sub_u32_e32 v1, v1, v3
	v_add_u32_e32 v5, 1, v2
	v_cmp_ge_u32_e32 vcc, v1, v0
	v_sub_u32_e32 v3, v1, v0
	s_nop 0
	v_cndmask_b32_e32 v2, v2, v5, vcc
	v_cndmask_b32_e32 v1, v1, v3, vcc
	v_add_u32_e32 v3, 1, v2
	v_cmp_ge_u32_e32 vcc, v1, v0
	s_nop 1
	v_cndmask_b32_e32 v2, v2, v3, vcc
	v_mul_lo_u32 v1, v0, v2
	v_add_u32_e32 v0, v1, v0
	v_mov_b32_e32 v30, v0
	v_cmp_ne_u32_e32 vcc, v4, v0
	v_mov_b64_e32 v[0:1], s[10:11]
	s_and_saveexec_b64 s[8:9], vcc
	s_cbranch_execz .LBB0_389
	v_mov_b32_e32 v0, 0
	global_load_dword v1, v0, s[10:11] offset:-256 sc1
	s_mov_b64 s[12:13], 0
	s_waitcnt vmcnt(0)
	v_cmp_lt_u32_e32 vcc, v1, v30
	s_and_saveexec_b64 s[48:49], vcc
	s_cbranch_execz .LBB0_388
	s_add_u32 s34, s94, 0x40200
	s_addc_u32 s35, s95, 0
	s_mov_b32 s18, 1
	s_mov_b64 s[58:59], 0
	s_branch .LBB0_381

; __device__ __forceinline__ unsigned xb_ld(unsigned* p)              { return __hip_atomic_load(p, __ATOMIC_RELAXED, __HIP_MEMORY_SCOPE_AGENT); }
; #define XB_SPIN(cond, bar) do { unsigned _sp = 0; while (cond) { __builtin_amdgcn_s_sleep(1); \
;     if ((++_sp & 255u) == 0u) { if (xb_ld(&(bar)[XB_TMO])) break; if (_sp > XB_SPIN_CAP) { atomicAdd(&(bar)[XB_TMO], 1u); break; } } } } while (0)
; __device__ __forceinline__ void xcd_barrier(const XcdBarrier& b) {
;     ...
;             else XB_SPIN(xb_ld(&bar[XB_TOPGEN]) == tg, bar);
.LBB0_383:
	global_load_dword v1, v0, s[10:11] offset:-256 sc1
	s_add_i32 s18, s18, 1
	s_mov_b64 s[12:13], -1
	s_waitcnt vmcnt(0)
	v_cmp_ge_u32_e32 vcc, v1, v30
	s_orn2_b64 s[80:81], vcc, exec
	s_branch .LBB0_380

; __device__ __forceinline__ unsigned xb_ld(unsigned* p)              { return __hip_atomic_load(p, __ATOMIC_RELAXED, __HIP_MEMORY_SCOPE_AGENT); }
; __device__ __forceinline__ unsigned xb_add(unsigned* p, unsigned v) { return __hip_atomic_fetch_add(p, v, __ATOMIC_RELAXED, __HIP_MEMORY_SCOPE_AGENT); }
; #define XB_SPIN(cond, bar) do { unsigned _sp = 0; while (cond) { __builtin_amdgcn_s_sleep(1); \
;     if ((++_sp & 255u) == 0u) { if (xb_ld(&(bar)[XB_TMO])) break; if (_sp > XB_SPIN_CAP) { atomicAdd(&(bar)[XB_TMO], 1u); break; } } } } while (0)
; __device__ __forceinline__ void xcd_barrier(const XcdBarrier& b) {
;     ...
;             const unsigned og = xb_add(&bar[XB_TOP], 1u);
;             const unsigned tg = og / nx;
;             if (og + 1u == (tg + 1u) * nx) xb_add(&bar[XB_TOPGEN], 1u);
;             else XB_SPIN(xb_ld(&bar[XB_TOPGEN]) == tg, bar);
.LBB0_501:
	s_or_b64 exec, exec, s[8:9]
	v_cvt_f32_u32_e32 v3, v0
	s_waitcnt vmcnt(0)
	v_readfirstlane_b32 s6, v2
	s_add_u32 s8, s94, 0x43500
	s_addc_u32 s9, s95, 0
	v_rcp_iflag_f32_e32 v3, v3
	v_add_u32_e32 v1, s6, v1
	v_add_u32_e32 v4, 1, v1
	s_mov_b64 s[10:11], -1
	v_mul_f32_e32 v2, 0x4f7ffffe, v3
	v_cvt_u32_f32_e32 v2, v2
	v_sub_u32_e32 v3, 0, v0
	v_mul_lo_u32 v3, v3, v2
	v_mul_hi_u32 v3, v2, v3
	v_add_u32_e32 v2, v2, v3
	v_mul_hi_u32 v2, v1, v2
	v_mul_lo_u32 v3, v2, v0
	v_sub_u32_e32 v1, v1, v3
	v_add_u32_e32 v5, 1, v2
	v_cmp_ge_u32_e32 vcc, v1, v0
	v_sub_u32_e32 v3, v1, v0
	s_nop 0
	v_cndmask_b32_e32 v2, v2, v5, vcc
	v_cndmask_b32_e32 v1, v1, v3, vcc
	v_add_u32_e32 v3, 1, v2
	v_cmp_ge_u32_e32 vcc, v1, v0
	s_nop 1
	v_cndmask_b32_e32 v2, v2, v3, vcc
	v_mul_lo_u32 v1, v0, v2
	v_add_u32_e32 v0, v1, v0
	v_mov_b32_e32 v30, v0
	v_cmp_ne_u32_e32 vcc, v4, v0
	v_mov_b64_e32 v[0:1], s[8:9]
	s_and_saveexec_b64 s[6:7], vcc
	s_cbranch_execz .LBB0_513
	v_mov_b32_e32 v0, 0
	global_load_dword v1, v0, s[8:9] offset:-256 sc1
	s_mov_b64 s[12:13], 0
	s_waitcnt vmcnt(0)
	v_cmp_lt_u32_e32 vcc, v1, v30
	s_and_saveexec_b64 s[34:35], vcc
	s_cbranch_execz .LBB0_512
	s_add_u32 s10, s94, 0x40200
	s_addc_u32 s11, s95, 0
	s_mov_b32 s18, 1
	s_mov_b64 s[48:49], 0
	s_branch .LBB0_505

; __device__ __forceinline__ unsigned xb_ld(unsigned* p)              { return __hip_atomic_load(p, __ATOMIC_RELAXED, __HIP_MEMORY_SCOPE_AGENT); }
; #define XB_SPIN(cond, bar) do { unsigned _sp = 0; while (cond) { __builtin_amdgcn_s_sleep(1); \
;     if ((++_sp & 255u) == 0u) { if (xb_ld(&(bar)[XB_TMO])) break; if (_sp > XB_SPIN_CAP) { atomicAdd(&(bar)[XB_TMO], 1u); break; } } } } while (0)
; __device__ __forceinline__ void xcd_barrier(const XcdBarrier& b) {
;     ...
;             else XB_SPIN(xb_ld(&bar[XB_TOPGEN]) == tg, bar);
.LBB0_507:
	global_load_dword v1, v0, s[8:9] offset:-256 sc1
	s_add_i32 s18, s18, 1
	s_mov_b64 s[12:13], -1
	s_waitcnt vmcnt(0)
	v_cmp_ge_u32_e32 vcc, v1, v30
	s_orn2_b64 s[58:59], vcc, exec
	s_branch .LBB0_504

; __device__ __forceinline__ unsigned xb_ld(unsigned* p)              { return __hip_atomic_load(p, __ATOMIC_RELAXED, __HIP_MEMORY_SCOPE_AGENT); }
; __device__ __forceinline__ unsigned xb_add(unsigned* p, unsigned v) { return __hip_atomic_fetch_add(p, v, __ATOMIC_RELAXED, __HIP_MEMORY_SCOPE_AGENT); }
; #define XB_SPIN(cond, bar) do { unsigned _sp = 0; while (cond) { __builtin_amdgcn_s_sleep(1); \
;     if ((++_sp & 255u) == 0u) { if (xb_ld(&(bar)[XB_TMO])) break; if (_sp > XB_SPIN_CAP) { atomicAdd(&(bar)[XB_TMO], 1u); break; } } } } while (0)
; __device__ __forceinline__ void xcd_barrier(const XcdBarrier& b) {
;     ...
;         const unsigned old = xb_add(&bar[XB_XSUB(b.x)], 1u);
;         const unsigned gen = old / nloc;
;         if (old + 1u == (gen + 1u) * nloc) {
;             __builtin_amdgcn_fence(__ATOMIC_RELEASE, "agent");
;             asm volatile("s_waitcnt vmcnt(0)" ::: "memory");
;             const unsigned og = xb_add(&bar[XB_TOP], 1u);
;             const unsigned tg = og / nx;
;             if (og + 1u == (tg + 1u) * nx) xb_add(&bar[XB_TOPGEN], 1u);
;             else XB_SPIN(xb_ld(&bar[XB_TOPGEN]) == tg, bar);
;             __builtin_amdgcn_fence(__ATOMIC_ACQUIRE, "agent");
;             xb_add(&bar[XB_XGEN(b.x)], 1u);
;             asm volatile("s_waitcnt vmcnt(0)" ::: "memory");
;         } else {
;             XB_SPIN(xb_ld(&bar[XB_XGEN(b.x)]) == gen, bar);
.LBB0_578:
	s_or_b64 exec, exec, s[10:11]
	v_cvt_f32_u32_e32 v4, v2
	s_waitcnt vmcnt(0)
	v_readfirstlane_b32 s8, v3
	v_sub_u32_e32 v3, 0, v2
	v_rcp_iflag_f32_e32 v4, v4
	v_add_u32_e32 v5, s8, v1
	v_mul_f32_e32 v4, 0x4f7ffffe, v4
	v_cvt_u32_f32_e32 v4, v4
	v_mul_lo_u32 v1, v3, v4
	v_mul_hi_u32 v1, v4, v1
	v_add_u32_e32 v1, v4, v1
	v_mul_hi_u32 v1, v5, v1
	v_mul_lo_u32 v3, v1, v2
	v_sub_u32_e32 v3, v5, v3
	v_add_u32_e32 v4, 1, v1
	v_cmp_ge_u32_e32 vcc, v3, v2
	s_nop 1
	v_cndmask_b32_e32 v1, v1, v4, vcc
	v_sub_u32_e32 v4, v3, v2
	v_cndmask_b32_e32 v3, v3, v4, vcc
	v_add_u32_e32 v4, 1, v1
	v_cmp_ge_u32_e32 vcc, v3, v2
	v_add_u32_e32 v3, 1, v5
	s_nop 0
	v_cndmask_b32_e32 v1, v1, v4, vcc
	v_mul_lo_u32 v4, v2, v1
	v_add_u32_e32 v2, v4, v2
	v_cmp_ne_u32_e32 vcc, v3, v2
	s_and_saveexec_b64 s[8:9], vcc
	s_xor_b64 s[8:9], exec, s[8:9]
	s_cbranch_execz .LBB0_592
	s_waitcnt lgkmcnt(0)
	s_add_u32 s38, s94, 0x43400
	s_addc_u32 s39, s95, 0
	v_mad_u32_u24 v1, v1, v0, v0
	v_mov_b32_e32 v0, 0
	global_load_dword v0, v0, s[38:39] sc1
	s_waitcnt vmcnt(0)
	v_cmp_lt_u32_e32 vcc, v0, v1
	s_and_saveexec_b64 s[10:11], vcc
	s_cbranch_execz .LBB0_591
	s_add_u32 s34, s94, 0x40200
	s_addc_u32 s35, s95, 0
	s_mov_b32 s18, 1
	s_mov_b64 s[42:43], 0
	v_mov_b32_e32 v0, 0
	s_branch .LBB0_582

; __device__ __forceinline__ unsigned xb_ld(unsigned* p)              { return __hip_atomic_load(p, __ATOMIC_RELAXED, __HIP_MEMORY_SCOPE_AGENT); }
; #define XB_SPIN(cond, bar) do { unsigned _sp = 0; while (cond) { __builtin_amdgcn_s_sleep(1); \
;     if ((++_sp & 255u) == 0u) { if (xb_ld(&(bar)[XB_TMO])) break; if (_sp > XB_SPIN_CAP) { atomicAdd(&(bar)[XB_TMO], 1u); break; } } } } while (0)
; __device__ __forceinline__ void xcd_barrier(const XcdBarrier& b) {
;     ...
;             XB_SPIN(xb_ld(&bar[XB_XGEN(b.x)]) == gen, bar);
.LBB0_584:
	global_load_dword v2, v0, s[38:39] sc1
	s_add_i32 s18, s18, 1
	s_mov_b64 s[14:15], -1
	s_waitcnt vmcnt(0)
	v_cmp_ge_u32_e32 vcc, v2, v1
	s_orn2_b64 s[12:13], vcc, exec
	s_branch .LBB0_581

; __device__ __forceinline__ unsigned xb_ld(unsigned* p)              { return __hip_atomic_load(p, __ATOMIC_RELAXED, __HIP_MEMORY_SCOPE_AGENT); }
; __device__ __forceinline__ unsigned xb_add(unsigned* p, unsigned v) { return __hip_atomic_fetch_add(p, v, __ATOMIC_RELAXED, __HIP_MEMORY_SCOPE_AGENT); }
; #define XB_SPIN(cond, bar) do { unsigned _sp = 0; while (cond) { __builtin_amdgcn_s_sleep(1); \
;     if ((++_sp & 255u) == 0u) { if (xb_ld(&(bar)[XB_TMO])) break; if (_sp > XB_SPIN_CAP) { atomicAdd(&(bar)[XB_TMO], 1u); break; } } } } while (0)
; __device__ __forceinline__ void xcd_barrier(const XcdBarrier& b) {
;     ...
;             const unsigned og = xb_add(&bar[XB_TOP], 1u);
;             const unsigned tg = og / nx;
;             if (og + 1u == (tg + 1u) * nx) xb_add(&bar[XB_TOPGEN], 1u);
;             else XB_SPIN(xb_ld(&bar[XB_TOPGEN]) == tg, bar);
.LBB0_595:
	s_or_b64 exec, exec, s[12:13]
	v_cvt_f32_u32_e32 v3, v0
	s_waitcnt vmcnt(0)
	v_readfirstlane_b32 s10, v2
	s_add_u32 s34, s94, 0x43500
	s_addc_u32 s35, s95, 0
	v_rcp_iflag_f32_e32 v3, v3
	v_add_u32_e32 v1, s10, v1
	v_add_u32_e32 v4, 1, v1
	s_mov_b64 s[12:13], -1
	v_mul_f32_e32 v2, 0x4f7ffffe, v3
	v_cvt_u32_f32_e32 v2, v2
	v_sub_u32_e32 v3, 0, v0
	v_mul_lo_u32 v3, v3, v2
	v_mul_hi_u32 v3, v2, v3
	v_add_u32_e32 v2, v2, v3
	v_mul_hi_u32 v2, v1, v2
	v_mul_lo_u32 v3, v2, v0
	v_sub_u32_e32 v1, v1, v3
	v_add_u32_e32 v5, 1, v2
	v_cmp_ge_u32_e32 vcc, v1, v0
	v_sub_u32_e32 v3, v1, v0
	s_nop 0
	v_cndmask_b32_e32 v2, v2, v5, vcc
	v_cndmask_b32_e32 v1, v1, v3, vcc
	v_add_u32_e32 v3, 1, v2
	v_cmp_ge_u32_e32 vcc, v1, v0
	s_nop 1
	v_cndmask_b32_e32 v2, v2, v3, vcc
	v_mul_lo_u32 v1, v0, v2
	v_add_u32_e32 v0, v1, v0
	v_mov_b32_e32 v30, v0
	v_cmp_ne_u32_e32 vcc, v4, v0
	v_mov_b64_e32 v[0:1], s[34:35]
	s_and_saveexec_b64 s[10:11], vcc
	s_cbranch_execz .LBB0_607
	v_mov_b32_e32 v0, 0
	global_load_dword v1, v0, s[34:35] offset:-256 sc1
	s_mov_b64 s[12:13], 0
	s_waitcnt vmcnt(0)
	v_cmp_lt_u32_e32 vcc, v1, v30
	s_and_saveexec_b64 s[42:43], vcc
	s_cbranch_execz .LBB0_606
	s_add_u32 s38, s94, 0x40200
	s_addc_u32 s39, s95, 0
	s_mov_b32 s18, 1
	s_mov_b64 s[48:49], 0
	s_branch .LBB0_599

; __device__ __forceinline__ unsigned xb_ld(unsigned* p)              { return __hip_atomic_load(p, __ATOMIC_RELAXED, __HIP_MEMORY_SCOPE_AGENT); }
; #define XB_SPIN(cond, bar) do { unsigned _sp = 0; while (cond) { __builtin_amdgcn_s_sleep(1); \
;     if ((++_sp & 255u) == 0u) { if (xb_ld(&(bar)[XB_TMO])) break; if (_sp > XB_SPIN_CAP) { atomicAdd(&(bar)[XB_TMO], 1u); break; } } } } while (0)
; __device__ __forceinline__ void xcd_barrier(const XcdBarrier& b) {
;     ...
;             else XB_SPIN(xb_ld(&bar[XB_TOPGEN]) == tg, bar);
.LBB0_601:
	global_load_dword v1, v0, s[34:35] offset:-256 sc1
	s_add_i32 s18, s18, 1
	s_mov_b64 s[12:13], -1
	s_waitcnt vmcnt(0)
	v_cmp_ge_u32_e32 vcc, v1, v30
	s_orn2_b64 s[56:57], vcc, exec
	s_branch .LBB0_598

; __device__ __forceinline__ unsigned xb_ld(unsigned* p)              { return __hip_atomic_load(p, __ATOMIC_RELAXED, __HIP_MEMORY_SCOPE_AGENT); }
; __device__ __forceinline__ unsigned xb_add(unsigned* p, unsigned v) { return __hip_atomic_fetch_add(p, v, __ATOMIC_RELAXED, __HIP_MEMORY_SCOPE_AGENT); }
; #define XB_SPIN(cond, bar) do { unsigned _sp = 0; while (cond) { __builtin_amdgcn_s_sleep(1); \
;     if ((++_sp & 255u) == 0u) { if (xb_ld(&(bar)[XB_TMO])) break; if (_sp > XB_SPIN_CAP) { atomicAdd(&(bar)[XB_TMO], 1u); break; } } } } while (0)
; __device__ __forceinline__ void xcd_barrier(const XcdBarrier& b) {
;     ...
;             const unsigned og = xb_add(&bar[XB_TOP], 1u);
;             const unsigned tg = og / nx;
;             if (og + 1u == (tg + 1u) * nx) xb_add(&bar[XB_TOPGEN], 1u);
;             else XB_SPIN(xb_ld(&bar[XB_TOPGEN]) == tg, bar);
.LBB0_718:
	s_or_b64 exec, exec, s[10:11]
	v_cvt_f32_u32_e32 v3, v0
	s_waitcnt vmcnt(0)
	v_readfirstlane_b32 s8, v2
	s_add_u32 s10, s94, 0x43500
	s_addc_u32 s11, s95, 0
	v_rcp_iflag_f32_e32 v3, v3
	v_add_u32_e32 v1, s8, v1
	v_add_u32_e32 v4, 1, v1
	s_mov_b64 s[12:13], -1
	v_mul_f32_e32 v2, 0x4f7ffffe, v3
	v_cvt_u32_f32_e32 v2, v2
	v_sub_u32_e32 v3, 0, v0
	v_mul_lo_u32 v3, v3, v2
	v_mul_hi_u32 v3, v2, v3
	v_add_u32_e32 v2, v2, v3
	v_mul_hi_u32 v2, v1, v2
	v_mul_lo_u32 v3, v2, v0
	v_sub_u32_e32 v1, v1, v3
	v_add_u32_e32 v5, 1, v2
	v_cmp_ge_u32_e32 vcc, v1, v0
	v_sub_u32_e32 v3, v1, v0
	s_nop 0
	v_cndmask_b32_e32 v2, v2, v5, vcc
	v_cndmask_b32_e32 v1, v1, v3, vcc
	v_add_u32_e32 v3, 1, v2
	v_cmp_ge_u32_e32 vcc, v1, v0
	s_nop 1
	v_cndmask_b32_e32 v2, v2, v3, vcc
	v_mul_lo_u32 v1, v0, v2
	v_add_u32_e32 v0, v1, v0
	v_mov_b32_e32 v30, v0
	v_cmp_ne_u32_e32 vcc, v4, v0
	v_mov_b64_e32 v[0:1], s[10:11]
	s_and_saveexec_b64 s[8:9], vcc
	s_cbranch_execz .LBB0_730
	v_mov_b32_e32 v0, 0
	global_load_dword v1, v0, s[10:11] offset:-256 sc1
	s_mov_b64 s[12:13], 0
	s_waitcnt vmcnt(0)
	v_cmp_lt_u32_e32 vcc, v1, v30
	s_and_saveexec_b64 s[38:39], vcc
	s_cbranch_execz .LBB0_729
	s_add_u32 s34, s94, 0x40200
	s_addc_u32 s35, s95, 0
	s_mov_b32 s18, 1
	s_mov_b64 s[42:43], 0
	s_branch .LBB0_722

; __device__ __forceinline__ unsigned xb_ld(unsigned* p)              { return __hip_atomic_load(p, __ATOMIC_RELAXED, __HIP_MEMORY_SCOPE_AGENT); }
; #define XB_SPIN(cond, bar) do { unsigned _sp = 0; while (cond) { __builtin_amdgcn_s_sleep(1); \
;     if ((++_sp & 255u) == 0u) { if (xb_ld(&(bar)[XB_TMO])) break; if (_sp > XB_SPIN_CAP) { atomicAdd(&(bar)[XB_TMO], 1u); break; } } } } while (0)
; __device__ __forceinline__ void xcd_barrier(const XcdBarrier& b) {
;     ...
;             else XB_SPIN(xb_ld(&bar[XB_TOPGEN]) == tg, bar);
.LBB0_724:
	global_load_dword v1, v0, s[10:11] offset:-256 sc1
	s_add_i32 s18, s18, 1
	s_mov_b64 s[12:13], -1
	s_waitcnt vmcnt(0)
	v_cmp_ge_u32_e32 vcc, v1, v30
	s_orn2_b64 s[54:55], vcc, exec
	s_branch .LBB0_721

; __device__ __forceinline__ unsigned xb_ld(unsigned* p)              { return __hip_atomic_load(p, __ATOMIC_RELAXED, __HIP_MEMORY_SCOPE_AGENT); }
; __device__ __forceinline__ unsigned xb_add(unsigned* p, unsigned v) { return __hip_atomic_fetch_add(p, v, __ATOMIC_RELAXED, __HIP_MEMORY_SCOPE_AGENT); }
; #define XB_SPIN(cond, bar) do { unsigned _sp = 0; while (cond) { __builtin_amdgcn_s_sleep(1); \
;     if ((++_sp & 255u) == 0u) { if (xb_ld(&(bar)[XB_TMO])) break; if (_sp > XB_SPIN_CAP) { atomicAdd(&(bar)[XB_TMO], 1u); break; } } } } while (0)
; __device__ __forceinline__ void xcd_barrier(const XcdBarrier& b) {
;     ...
;         const unsigned old = xb_add(&bar[XB_XSUB(b.x)], 1u);
;         const unsigned gen = old / nloc;
;         if (old + 1u == (gen + 1u) * nloc) {
;             __builtin_amdgcn_fence(__ATOMIC_RELEASE, "agent");
;             asm volatile("s_waitcnt vmcnt(0)" ::: "memory");
;             const unsigned og = xb_add(&bar[XB_TOP], 1u);
;             const unsigned tg = og / nx;
;             if (og + 1u == (tg + 1u) * nx) xb_add(&bar[XB_TOPGEN], 1u);
;             else XB_SPIN(xb_ld(&bar[XB_TOPGEN]) == tg, bar);
;             __builtin_amdgcn_fence(__ATOMIC_ACQUIRE, "agent");
;             xb_add(&bar[XB_XGEN(b.x)], 1u);
;             asm volatile("s_waitcnt vmcnt(0)" ::: "memory");
;         } else {
;             XB_SPIN(xb_ld(&bar[XB_XGEN(b.x)]) == gen, bar);
.LBB0_779:
	s_or_b64 exec, exec, s[12:13]
	v_cvt_f32_u32_e32 v4, v2
	s_waitcnt vmcnt(0)
	v_readfirstlane_b32 s10, v3
	v_sub_u32_e32 v3, 0, v2
	v_rcp_iflag_f32_e32 v4, v4
	v_add_u32_e32 v5, s10, v1
	v_mul_f32_e32 v4, 0x4f7ffffe, v4
	v_cvt_u32_f32_e32 v4, v4
	v_mul_lo_u32 v1, v3, v4
	v_mul_hi_u32 v1, v4, v1
	v_add_u32_e32 v1, v4, v1
	v_mul_hi_u32 v1, v5, v1
	v_mul_lo_u32 v3, v1, v2
	v_sub_u32_e32 v3, v5, v3
	v_add_u32_e32 v4, 1, v1
	v_cmp_ge_u32_e32 vcc, v3, v2
	s_nop 1
	v_cndmask_b32_e32 v1, v1, v4, vcc
	v_sub_u32_e32 v4, v3, v2
	v_cndmask_b32_e32 v3, v3, v4, vcc
	v_add_u32_e32 v4, 1, v1
	v_cmp_ge_u32_e32 vcc, v3, v2
	v_add_u32_e32 v3, 1, v5
	s_nop 0
	v_cndmask_b32_e32 v1, v1, v4, vcc
	v_mul_lo_u32 v4, v2, v1
	v_add_u32_e32 v2, v4, v2
	v_cmp_ne_u32_e32 vcc, v3, v2
	s_and_saveexec_b64 s[10:11], vcc
	s_xor_b64 s[10:11], exec, s[10:11]
	s_cbranch_execz .LBB0_793
	s_waitcnt lgkmcnt(0)
	s_add_u32 s42, s94, 0x43400
	s_addc_u32 s43, s95, 0
	v_mad_u32_u24 v1, v1, v0, v0
	v_mov_b32_e32 v0, 0
	global_load_dword v0, v0, s[42:43] sc1
	s_waitcnt vmcnt(0)
	v_cmp_lt_u32_e32 vcc, v0, v1
	s_and_saveexec_b64 s[34:35], vcc
	s_cbranch_execz .LBB0_792
	s_add_u32 s38, s94, 0x40200
	s_addc_u32 s39, s95, 0
	s_mov_b32 s19, 1
	s_mov_b64 s[48:49], 0
	v_mov_b32_e32 v0, 0
	s_branch .LBB0_783

; __device__ __forceinline__ unsigned xb_ld(unsigned* p)              { return __hip_atomic_load(p, __ATOMIC_RELAXED, __HIP_MEMORY_SCOPE_AGENT); }
; #define XB_SPIN(cond, bar) do { unsigned _sp = 0; while (cond) { __builtin_amdgcn_s_sleep(1); \
;     if ((++_sp & 255u) == 0u) { if (xb_ld(&(bar)[XB_TMO])) break; if (_sp > XB_SPIN_CAP) { atomicAdd(&(bar)[XB_TMO], 1u); break; } } } } while (0)
; __device__ __forceinline__ void xcd_barrier(const XcdBarrier& b) {
;     ...
;             XB_SPIN(xb_ld(&bar[XB_XGEN(b.x)]) == gen, bar);
.LBB0_785:
	global_load_dword v2, v0, s[42:43] sc1
	s_add_i32 s19, s19, 1
	s_mov_b64 s[14:15], -1
	s_waitcnt vmcnt(0)
	v_cmp_ge_u32_e32 vcc, v2, v1
	s_orn2_b64 s[12:13], vcc, exec
	s_branch .LBB0_782

; __device__ __forceinline__ unsigned xb_ld(unsigned* p)              { return __hip_atomic_load(p, __ATOMIC_RELAXED, __HIP_MEMORY_SCOPE_AGENT); }
; __device__ __forceinline__ unsigned xb_add(unsigned* p, unsigned v) { return __hip_atomic_fetch_add(p, v, __ATOMIC_RELAXED, __HIP_MEMORY_SCOPE_AGENT); }
; #define XB_SPIN(cond, bar) do { unsigned _sp = 0; while (cond) { __builtin_amdgcn_s_sleep(1); \
;     if ((++_sp & 255u) == 0u) { if (xb_ld(&(bar)[XB_TMO])) break; if (_sp > XB_SPIN_CAP) { atomicAdd(&(bar)[XB_TMO], 1u); break; } } } } while (0)
; __device__ __forceinline__ void xcd_barrier(const XcdBarrier& b) {
;     ...
;             const unsigned og = xb_add(&bar[XB_TOP], 1u);
;             const unsigned tg = og / nx;
;             if (og + 1u == (tg + 1u) * nx) xb_add(&bar[XB_TOPGEN], 1u);
;             else XB_SPIN(xb_ld(&bar[XB_TOPGEN]) == tg, bar);
.LBB0_796:
	s_or_b64 exec, exec, s[14:15]
	v_cvt_f32_u32_e32 v3, v0
	s_waitcnt vmcnt(0)
	v_readfirstlane_b32 s12, v2
	s_add_u32 s38, s94, 0x43500
	s_addc_u32 s39, s95, 0
	v_rcp_iflag_f32_e32 v3, v3
	v_add_u32_e32 v1, s12, v1
	v_add_u32_e32 v4, 1, v1
	s_mov_b64 s[12:13], -1
	v_mul_f32_e32 v2, 0x4f7ffffe, v3
	v_cvt_u32_f32_e32 v2, v2
	v_sub_u32_e32 v3, 0, v0
	v_mul_lo_u32 v3, v3, v2
	v_mul_hi_u32 v3, v2, v3
	v_add_u32_e32 v2, v2, v3
	v_mul_hi_u32 v2, v1, v2
	v_mul_lo_u32 v3, v2, v0
	v_sub_u32_e32 v1, v1, v3
	v_add_u32_e32 v5, 1, v2
	v_cmp_ge_u32_e32 vcc, v1, v0
	v_sub_u32_e32 v3, v1, v0
	s_nop 0
	v_cndmask_b32_e32 v2, v2, v5, vcc
	v_cndmask_b32_e32 v1, v1, v3, vcc
	v_add_u32_e32 v3, 1, v2
	v_cmp_ge_u32_e32 vcc, v1, v0
	s_nop 1
	v_cndmask_b32_e32 v2, v2, v3, vcc
	v_mul_lo_u32 v1, v0, v2
	v_add_u32_e32 v0, v1, v0
	v_mov_b32_e32 v30, v0
	v_cmp_ne_u32_e32 vcc, v4, v0
	v_mov_b64_e32 v[0:1], s[38:39]
	s_and_saveexec_b64 s[34:35], vcc
	s_cbranch_execz .LBB0_808
	v_mov_b32_e32 v0, 0
	global_load_dword v1, v0, s[38:39] offset:-256 sc1
	s_mov_b64 s[12:13], 0
	s_waitcnt vmcnt(0)
	v_cmp_lt_u32_e32 vcc, v1, v30
	s_and_saveexec_b64 s[48:49], vcc
	s_cbranch_execz .LBB0_807
	s_add_u32 s42, s94, 0x40200
	s_addc_u32 s43, s95, 0
	s_mov_b32 s19, 1
	s_mov_b64 s[52:53], 0
	s_branch .LBB0_800

; __device__ __forceinline__ unsigned xb_ld(unsigned* p)              { return __hip_atomic_load(p, __ATOMIC_RELAXED, __HIP_MEMORY_SCOPE_AGENT); }
; #define XB_SPIN(cond, bar) do { unsigned _sp = 0; while (cond) { __builtin_amdgcn_s_sleep(1); \
;     if ((++_sp & 255u) == 0u) { if (xb_ld(&(bar)[XB_TMO])) break; if (_sp > XB_SPIN_CAP) { atomicAdd(&(bar)[XB_TMO], 1u); break; } } } } while (0)
; __device__ __forceinline__ void xcd_barrier(const XcdBarrier& b) {
;     ...
;             else XB_SPIN(xb_ld(&bar[XB_TOPGEN]) == tg, bar);
.LBB0_802:
	global_load_dword v1, v0, s[38:39] offset:-256 sc1
	s_add_i32 s19, s19, 1
	s_mov_b64 s[12:13], -1
	s_waitcnt vmcnt(0)
	v_cmp_ge_u32_e32 vcc, v1, v30
	s_orn2_b64 s[56:57], vcc, exec
	s_branch .LBB0_799

; __device__ __forceinline__ unsigned xb_ld(unsigned* p)              { return __hip_atomic_load(p, __ATOMIC_RELAXED, __HIP_MEMORY_SCOPE_AGENT); }
; __device__ __forceinline__ unsigned xb_add(unsigned* p, unsigned v) { return __hip_atomic_fetch_add(p, v, __ATOMIC_RELAXED, __HIP_MEMORY_SCOPE_AGENT); }
; #define XB_SPIN(cond, bar) do { unsigned _sp = 0; while (cond) { __builtin_amdgcn_s_sleep(1); \
;     if ((++_sp & 255u) == 0u) { if (xb_ld(&(bar)[XB_TMO])) break; if (_sp > XB_SPIN_CAP) { atomicAdd(&(bar)[XB_TMO], 1u); break; } } } } while (0)
; __device__ __forceinline__ void xcd_barrier(const XcdBarrier& b) {
;     ...
;         const unsigned old = xb_add(&bar[XB_XSUB(b.x)], 1u);
;         const unsigned gen = old / nloc;
;         if (old + 1u == (gen + 1u) * nloc) {
;             __builtin_amdgcn_fence(__ATOMIC_RELEASE, "agent");
;             asm volatile("s_waitcnt vmcnt(0)" ::: "memory");
;             const unsigned og = xb_add(&bar[XB_TOP], 1u);
;             const unsigned tg = og / nx;
;             if (og + 1u == (tg + 1u) * nx) xb_add(&bar[XB_TOPGEN], 1u);
;             else XB_SPIN(xb_ld(&bar[XB_TOPGEN]) == tg, bar);
;             __builtin_amdgcn_fence(__ATOMIC_ACQUIRE, "agent");
;             xb_add(&bar[XB_XGEN(b.x)], 1u);
;             asm volatile("s_waitcnt vmcnt(0)" ::: "memory");
;         } else {
;             XB_SPIN(xb_ld(&bar[XB_XGEN(b.x)]) == gen, bar);
.LBB0_880:
	s_or_b64 exec, exec, s[8:9]
	v_cvt_f32_u32_e32 v4, v2
	s_waitcnt vmcnt(0)
	v_readfirstlane_b32 s6, v3
	v_sub_u32_e32 v3, 0, v2
	v_rcp_iflag_f32_e32 v4, v4
	v_add_u32_e32 v5, s6, v1
	v_mul_f32_e32 v4, 0x4f7ffffe, v4
	v_cvt_u32_f32_e32 v4, v4
	v_mul_lo_u32 v1, v3, v4
	v_mul_hi_u32 v1, v4, v1
	v_add_u32_e32 v1, v4, v1
	v_mul_hi_u32 v1, v5, v1
	v_mul_lo_u32 v3, v1, v2
	v_sub_u32_e32 v3, v5, v3
	v_add_u32_e32 v4, 1, v1
	v_cmp_ge_u32_e32 vcc, v3, v2
	s_nop 1
	v_cndmask_b32_e32 v1, v1, v4, vcc
	v_sub_u32_e32 v4, v3, v2
	v_cndmask_b32_e32 v3, v3, v4, vcc
	v_add_u32_e32 v4, 1, v1
	v_cmp_ge_u32_e32 vcc, v3, v2
	v_add_u32_e32 v3, 1, v5
	s_nop 0
	v_cndmask_b32_e32 v1, v1, v4, vcc
	v_mul_lo_u32 v4, v2, v1
	v_add_u32_e32 v2, v4, v2
	v_cmp_ne_u32_e32 vcc, v3, v2
	s_and_saveexec_b64 s[6:7], vcc
	s_xor_b64 s[6:7], exec, s[6:7]
	s_cbranch_execz .LBB0_894
	s_waitcnt lgkmcnt(0)
	s_add_u32 s16, s94, 0x43400
	s_addc_u32 s17, s95, 0
	v_mad_u32_u24 v1, v1, v0, v0
	v_mov_b32_e32 v0, 0
	global_load_dword v0, v0, s[16:17] sc1
	s_waitcnt vmcnt(0)
	v_cmp_lt_u32_e32 vcc, v0, v1
	s_and_saveexec_b64 s[8:9], vcc
	s_cbranch_execz .LBB0_893
	s_add_u32 s10, s94, 0x40200
	s_addc_u32 s11, s95, 0
	s_mov_b32 s21, 1
	s_mov_b64 s[18:19], 0
	v_mov_b32_e32 v0, 0
	s_branch .LBB0_884

; __device__ __forceinline__ unsigned xb_ld(unsigned* p)              { return __hip_atomic_load(p, __ATOMIC_RELAXED, __HIP_MEMORY_SCOPE_AGENT); }
; #define XB_SPIN(cond, bar) do { unsigned _sp = 0; while (cond) { __builtin_amdgcn_s_sleep(1); \
;     if ((++_sp & 255u) == 0u) { if (xb_ld(&(bar)[XB_TMO])) break; if (_sp > XB_SPIN_CAP) { atomicAdd(&(bar)[XB_TMO], 1u); break; } } } } while (0)
; __device__ __forceinline__ void xcd_barrier(const XcdBarrier& b) {
;     ...
;             XB_SPIN(xb_ld(&bar[XB_XGEN(b.x)]) == gen, bar);
.LBB0_886:
	global_load_dword v2, v0, s[16:17] sc1
	s_add_i32 s21, s21, 1
	s_mov_b64 s[14:15], -1
	s_waitcnt vmcnt(0)
	v_cmp_ge_u32_e32 vcc, v2, v1
	s_orn2_b64 s[12:13], vcc, exec
	s_branch .LBB0_883

; __device__ __forceinline__ unsigned xb_ld(unsigned* p)              { return __hip_atomic_load(p, __ATOMIC_RELAXED, __HIP_MEMORY_SCOPE_AGENT); }
; __device__ __forceinline__ unsigned xb_add(unsigned* p, unsigned v) { return __hip_atomic_fetch_add(p, v, __ATOMIC_RELAXED, __HIP_MEMORY_SCOPE_AGENT); }
; #define XB_SPIN(cond, bar) do { unsigned _sp = 0; while (cond) { __builtin_amdgcn_s_sleep(1); \
;     if ((++_sp & 255u) == 0u) { if (xb_ld(&(bar)[XB_TMO])) break; if (_sp > XB_SPIN_CAP) { atomicAdd(&(bar)[XB_TMO], 1u); break; } } } } while (0)
; __device__ __forceinline__ void xcd_barrier(const XcdBarrier& b) {
;     ...
;             const unsigned og = xb_add(&bar[XB_TOP], 1u);
;             const unsigned tg = og / nx;
;             if (og + 1u == (tg + 1u) * nx) xb_add(&bar[XB_TOPGEN], 1u);
;             else XB_SPIN(xb_ld(&bar[XB_TOPGEN]) == tg, bar);
.LBB0_897:
	s_or_b64 exec, exec, s[10:11]
	v_cvt_f32_u32_e32 v3, v0
	s_waitcnt vmcnt(0)
	v_readfirstlane_b32 s8, v2
	s_add_u32 s10, s94, 0x43500
	s_addc_u32 s11, s95, 0
	v_rcp_iflag_f32_e32 v3, v3
	v_add_u32_e32 v1, s8, v1
	v_add_u32_e32 v4, 1, v1
	s_mov_b64 s[12:13], -1
	v_mul_f32_e32 v2, 0x4f7ffffe, v3
	v_cvt_u32_f32_e32 v2, v2
	v_sub_u32_e32 v3, 0, v0
	v_mul_lo_u32 v3, v3, v2
	v_mul_hi_u32 v3, v2, v3
	v_add_u32_e32 v2, v2, v3
	v_mul_hi_u32 v2, v1, v2
	v_mul_lo_u32 v3, v2, v0
	v_sub_u32_e32 v1, v1, v3
	v_add_u32_e32 v5, 1, v2
	v_cmp_ge_u32_e32 vcc, v1, v0
	v_sub_u32_e32 v3, v1, v0
	s_nop 0
	v_cndmask_b32_e32 v2, v2, v5, vcc
	v_cndmask_b32_e32 v1, v1, v3, vcc
	v_add_u32_e32 v3, 1, v2
	v_cmp_ge_u32_e32 vcc, v1, v0
	s_nop 1
	v_cndmask_b32_e32 v2, v2, v3, vcc
	v_mul_lo_u32 v1, v0, v2
	v_add_u32_e32 v0, v1, v0
	v_mov_b32_e32 v30, v0
	v_cmp_ne_u32_e32 vcc, v4, v0
	v_mov_b64_e32 v[0:1], s[10:11]
	s_and_saveexec_b64 s[8:9], vcc
	s_cbranch_execz .LBB0_909
	v_mov_b32_e32 v0, 0
	global_load_dword v1, v0, s[10:11] offset:-256 sc1
	s_mov_b64 s[12:13], 0
	s_waitcnt vmcnt(0)
	v_cmp_lt_u32_e32 vcc, v1, v30
	s_and_saveexec_b64 s[18:19], vcc
	s_cbranch_execz .LBB0_908
	s_add_u32 s16, s94, 0x40200
	s_addc_u32 s17, s95, 0
	s_mov_b32 s21, 1
	s_mov_b64 s[24:25], 0
	s_branch .LBB0_901

; __device__ __forceinline__ unsigned xb_ld(unsigned* p)              { return __hip_atomic_load(p, __ATOMIC_RELAXED, __HIP_MEMORY_SCOPE_AGENT); }
; #define XB_SPIN(cond, bar) do { unsigned _sp = 0; while (cond) { __builtin_amdgcn_s_sleep(1); \
;     if ((++_sp & 255u) == 0u) { if (xb_ld(&(bar)[XB_TMO])) break; if (_sp > XB_SPIN_CAP) { atomicAdd(&(bar)[XB_TMO], 1u); break; } } } } while (0)
; __device__ __forceinline__ void xcd_barrier(const XcdBarrier& b) {
;     ...
;             else XB_SPIN(xb_ld(&bar[XB_TOPGEN]) == tg, bar);
.LBB0_903:
	global_load_dword v1, v0, s[10:11] offset:-256 sc1
	s_add_i32 s21, s21, 1
	s_mov_b64 s[12:13], -1
	s_waitcnt vmcnt(0)
	v_cmp_ge_u32_e32 vcc, v1, v30
	s_orn2_b64 s[38:39], vcc, exec
	s_branch .LBB0_900

; __device__ __forceinline__ unsigned xb_ld(unsigned* p)              { return __hip_atomic_load(p, __ATOMIC_RELAXED, __HIP_MEMORY_SCOPE_AGENT); }
; __device__ __forceinline__ unsigned xb_add(unsigned* p, unsigned v) { return __hip_atomic_fetch_add(p, v, __ATOMIC_RELAXED, __HIP_MEMORY_SCOPE_AGENT); }
; #define XB_SPIN(cond, bar) do { unsigned _sp = 0; while (cond) { __builtin_amdgcn_s_sleep(1); \
;     if ((++_sp & 255u) == 0u) { if (xb_ld(&(bar)[XB_TMO])) break; if (_sp > XB_SPIN_CAP) { atomicAdd(&(bar)[XB_TMO], 1u); break; } } } } while (0)
; __device__ __forceinline__ void xcd_barrier(const XcdBarrier& b) {
;     ...
;         const unsigned old = xb_add(&bar[XB_XSUB(b.x)], 1u);
;         const unsigned gen = old / nloc;
;         if (old + 1u == (gen + 1u) * nloc) {
;             __builtin_amdgcn_fence(__ATOMIC_RELEASE, "agent");
;             asm volatile("s_waitcnt vmcnt(0)" ::: "memory");
;             const unsigned og = xb_add(&bar[XB_TOP], 1u);
;             const unsigned tg = og / nx;
;             if (og + 1u == (tg + 1u) * nx) xb_add(&bar[XB_TOPGEN], 1u);
;             else XB_SPIN(xb_ld(&bar[XB_TOPGEN]) == tg, bar);
;             __builtin_amdgcn_fence(__ATOMIC_ACQUIRE, "agent");
;             xb_add(&bar[XB_XGEN(b.x)], 1u);
;             asm volatile("s_waitcnt vmcnt(0)" ::: "memory");
;         } else {
;             XB_SPIN(xb_ld(&bar[XB_XGEN(b.x)]) == gen, bar);
.LBB0_967:
	s_or_b64 exec, exec, s[8:9]
	v_cvt_f32_u32_e32 v4, v2
	s_waitcnt vmcnt(0)
	v_readfirstlane_b32 s6, v3
	v_sub_u32_e32 v3, 0, v2
	v_rcp_iflag_f32_e32 v4, v4
	v_add_u32_e32 v5, s6, v1
	v_mul_f32_e32 v4, 0x4f7ffffe, v4
	v_cvt_u32_f32_e32 v4, v4
	v_mul_lo_u32 v1, v3, v4
	v_mul_hi_u32 v1, v4, v1
	v_add_u32_e32 v1, v4, v1
	v_mul_hi_u32 v1, v5, v1
	v_mul_lo_u32 v3, v1, v2
	v_sub_u32_e32 v3, v5, v3
	v_add_u32_e32 v4, 1, v1
	v_cmp_ge_u32_e32 vcc, v3, v2
	s_nop 1
	v_cndmask_b32_e32 v1, v1, v4, vcc
	v_sub_u32_e32 v4, v3, v2
	v_cndmask_b32_e32 v3, v3, v4, vcc
	v_add_u32_e32 v4, 1, v1
	v_cmp_ge_u32_e32 vcc, v3, v2
	v_add_u32_e32 v3, 1, v5
	s_nop 0
	v_cndmask_b32_e32 v1, v1, v4, vcc
	v_mul_lo_u32 v4, v2, v1
	v_add_u32_e32 v2, v4, v2
	v_cmp_ne_u32_e32 vcc, v3, v2
	s_and_saveexec_b64 s[6:7], vcc
	s_xor_b64 s[6:7], exec, s[6:7]
	s_cbranch_execz .LBB0_981
	s_waitcnt lgkmcnt(0)
	s_add_u32 s42, s94, 0x43400
	s_addc_u32 s43, s95, 0
	v_mad_u32_u24 v1, v1, v0, v0
	v_mov_b32_e32 v0, 0
	global_load_dword v0, v0, s[42:43] sc1
	s_waitcnt vmcnt(0)
	v_cmp_lt_u32_e32 vcc, v0, v1
	s_and_saveexec_b64 s[8:9], vcc
	s_cbranch_execz .LBB0_980
	s_add_u32 s34, s94, 0x40200
	s_addc_u32 s35, s95, 0
	s_mov_b32 s20, 1
	s_mov_b64 s[44:45], 0
	v_mov_b32_e32 v0, 0
	s_branch .LBB0_971

; __device__ __forceinline__ unsigned xb_ld(unsigned* p)              { return __hip_atomic_load(p, __ATOMIC_RELAXED, __HIP_MEMORY_SCOPE_AGENT); }
; #define XB_SPIN(cond, bar) do { unsigned _sp = 0; while (cond) { __builtin_amdgcn_s_sleep(1); \
;     if ((++_sp & 255u) == 0u) { if (xb_ld(&(bar)[XB_TMO])) break; if (_sp > XB_SPIN_CAP) { atomicAdd(&(bar)[XB_TMO], 1u); break; } } } } while (0)
; __device__ __forceinline__ void xcd_barrier(const XcdBarrier& b) {
;     ...
;             XB_SPIN(xb_ld(&bar[XB_XGEN(b.x)]) == gen, bar);
.LBB0_973:
	global_load_dword v2, v0, s[42:43] sc1
	s_add_i32 s20, s20, 1
	s_mov_b64 s[14:15], -1
	s_waitcnt vmcnt(0)
	v_cmp_ge_u32_e32 vcc, v2, v1
	s_orn2_b64 s[12:13], vcc, exec
	s_branch .LBB0_970

; __device__ __forceinline__ unsigned xb_ld(unsigned* p)              { return __hip_atomic_load(p, __ATOMIC_RELAXED, __HIP_MEMORY_SCOPE_AGENT); }
; __device__ __forceinline__ unsigned xb_add(unsigned* p, unsigned v) { return __hip_atomic_fetch_add(p, v, __ATOMIC_RELAXED, __HIP_MEMORY_SCOPE_AGENT); }
; #define XB_SPIN(cond, bar) do { unsigned _sp = 0; while (cond) { __builtin_amdgcn_s_sleep(1); \
;     if ((++_sp & 255u) == 0u) { if (xb_ld(&(bar)[XB_TMO])) break; if (_sp > XB_SPIN_CAP) { atomicAdd(&(bar)[XB_TMO], 1u); break; } } } } while (0)
; __device__ __forceinline__ void xcd_barrier(const XcdBarrier& b) {
;     ...
;             const unsigned og = xb_add(&bar[XB_TOP], 1u);
;             const unsigned tg = og / nx;
;             if (og + 1u == (tg + 1u) * nx) xb_add(&bar[XB_TOPGEN], 1u);
;             else XB_SPIN(xb_ld(&bar[XB_TOPGEN]) == tg, bar);
.LBB0_984:
	s_or_b64 exec, exec, s[12:13]
	v_cvt_f32_u32_e32 v3, v0
	s_waitcnt vmcnt(0)
	v_readfirstlane_b32 s8, v2
	s_add_u32 s34, s94, 0x43500
	s_addc_u32 s35, s95, 0
	v_rcp_iflag_f32_e32 v3, v3
	v_add_u32_e32 v1, s8, v1
	v_add_u32_e32 v4, 1, v1
	s_mov_b64 s[12:13], -1
	v_mul_f32_e32 v2, 0x4f7ffffe, v3
	v_cvt_u32_f32_e32 v2, v2
	v_sub_u32_e32 v3, 0, v0
	v_mul_lo_u32 v3, v3, v2
	v_mul_hi_u32 v3, v2, v3
	v_add_u32_e32 v2, v2, v3
	v_mul_hi_u32 v2, v1, v2
	v_mul_lo_u32 v3, v2, v0
	v_sub_u32_e32 v1, v1, v3
	v_add_u32_e32 v5, 1, v2
	v_cmp_ge_u32_e32 vcc, v1, v0
	v_sub_u32_e32 v3, v1, v0
	s_nop 0
	v_cndmask_b32_e32 v2, v2, v5, vcc
	v_cndmask_b32_e32 v1, v1, v3, vcc
	v_add_u32_e32 v3, 1, v2
	v_cmp_ge_u32_e32 vcc, v1, v0
	s_nop 1
	v_cndmask_b32_e32 v2, v2, v3, vcc
	v_mul_lo_u32 v1, v0, v2
	v_add_u32_e32 v0, v1, v0
	v_mov_b32_e32 v30, v0
	v_cmp_ne_u32_e32 vcc, v4, v0
	v_mov_b64_e32 v[0:1], s[34:35]
	s_and_saveexec_b64 s[8:9], vcc
	s_cbranch_execz .LBB0_996
	v_mov_b32_e32 v0, 0
	global_load_dword v1, v0, s[34:35] offset:-256 sc1
	s_mov_b64 s[12:13], 0
	s_waitcnt vmcnt(0)
	v_cmp_lt_u32_e32 vcc, v1, v30
	s_and_saveexec_b64 s[44:45], vcc
	s_cbranch_execz .LBB0_995
	s_add_u32 s42, s94, 0x40200
	s_addc_u32 s43, s95, 0
	s_mov_b32 s20, 1
	s_mov_b64 s[46:47], 0
	s_branch .LBB0_988

; __device__ __forceinline__ unsigned xb_ld(unsigned* p)              { return __hip_atomic_load(p, __ATOMIC_RELAXED, __HIP_MEMORY_SCOPE_AGENT); }
; #define XB_SPIN(cond, bar) do { unsigned _sp = 0; while (cond) { __builtin_amdgcn_s_sleep(1); \
;     if ((++_sp & 255u) == 0u) { if (xb_ld(&(bar)[XB_TMO])) break; if (_sp > XB_SPIN_CAP) { atomicAdd(&(bar)[XB_TMO], 1u); break; } } } } while (0)
; __device__ __forceinline__ void xcd_barrier(const XcdBarrier& b) {
;     ...
;             else XB_SPIN(xb_ld(&bar[XB_TOPGEN]) == tg, bar);
.LBB0_990:
	global_load_dword v1, v0, s[34:35] offset:-256 sc1
	s_add_i32 s20, s20, 1
	s_mov_b64 s[12:13], -1
	s_waitcnt vmcnt(0)
	v_cmp_ge_u32_e32 vcc, v1, v30
	s_orn2_b64 s[50:51], vcc, exec
	s_branch .LBB0_987

; __device__ __forceinline__ unsigned xb_ld(unsigned* p)              { return __hip_atomic_load(p, __ATOMIC_RELAXED, __HIP_MEMORY_SCOPE_AGENT); }
; __device__ __forceinline__ unsigned xb_add(unsigned* p, unsigned v) { return __hip_atomic_fetch_add(p, v, __ATOMIC_RELAXED, __HIP_MEMORY_SCOPE_AGENT); }
; #define XB_SPIN(cond, bar) do { unsigned _sp = 0; while (cond) { __builtin_amdgcn_s_sleep(1); \
;     if ((++_sp & 255u) == 0u) { if (xb_ld(&(bar)[XB_TMO])) break; if (_sp > XB_SPIN_CAP) { atomicAdd(&(bar)[XB_TMO], 1u); break; } } } } while (0)
; __device__ __forceinline__ void xcd_barrier(const XcdBarrier& b) {
;     ...
;         const unsigned old = xb_add(&bar[XB_XSUB(b.x)], 1u);
;         const unsigned gen = old / nloc;
;         if (old + 1u == (gen + 1u) * nloc) {
;             __builtin_amdgcn_fence(__ATOMIC_RELEASE, "agent");
;             asm volatile("s_waitcnt vmcnt(0)" ::: "memory");
;             const unsigned og = xb_add(&bar[XB_TOP], 1u);
;             const unsigned tg = og / nx;
;             if (og + 1u == (tg + 1u) * nx) xb_add(&bar[XB_TOPGEN], 1u);
;             else XB_SPIN(xb_ld(&bar[XB_TOPGEN]) == tg, bar);
;             __builtin_amdgcn_fence(__ATOMIC_ACQUIRE, "agent");
;             xb_add(&bar[XB_XGEN(b.x)], 1u);
;             asm volatile("s_waitcnt vmcnt(0)" ::: "memory");
;         } else {
;             XB_SPIN(xb_ld(&bar[XB_XGEN(b.x)]) == gen, bar);
.LBB0_1035:
	s_or_b64 exec, exec, s[8:9]
	v_cvt_f32_u32_e32 v4, v2
	s_waitcnt vmcnt(0)
	v_readfirstlane_b32 s3, v3
	v_sub_u32_e32 v3, 0, v2
	v_rcp_iflag_f32_e32 v4, v4
	v_add_u32_e32 v5, s3, v1
	v_mul_f32_e32 v4, 0x4f7ffffe, v4
	v_cvt_u32_f32_e32 v4, v4
	v_mul_lo_u32 v1, v3, v4
	v_mul_hi_u32 v1, v4, v1
	v_add_u32_e32 v1, v4, v1
	v_mul_hi_u32 v1, v5, v1
	v_mul_lo_u32 v3, v1, v2
	v_sub_u32_e32 v3, v5, v3
	v_add_u32_e32 v4, 1, v1
	v_cmp_ge_u32_e32 vcc, v3, v2
	s_nop 1
	v_cndmask_b32_e32 v1, v1, v4, vcc
	v_sub_u32_e32 v4, v3, v2
	v_cndmask_b32_e32 v3, v3, v4, vcc
	v_add_u32_e32 v4, 1, v1
	v_cmp_ge_u32_e32 vcc, v3, v2
	v_add_u32_e32 v3, 1, v5
	s_nop 0
	v_cndmask_b32_e32 v1, v1, v4, vcc
	v_mul_lo_u32 v4, v2, v1
	v_add_u32_e32 v2, v4, v2
	v_cmp_ne_u32_e32 vcc, v3, v2
	s_and_saveexec_b64 s[6:7], vcc
	s_xor_b64 s[6:7], exec, s[6:7]
	s_cbranch_execz .LBB0_1049
	s_waitcnt lgkmcnt(0)
	s_add_u32 s16, s94, 0x43400
	s_addc_u32 s17, s95, 0
	v_mad_u32_u24 v1, v1, v0, v0
	v_mov_b32_e32 v0, 0
	global_load_dword v0, v0, s[16:17] sc1
	s_waitcnt vmcnt(0)
	v_cmp_lt_u32_e32 vcc, v0, v1
	s_and_saveexec_b64 s[8:9], vcc
	s_cbranch_execz .LBB0_1048
	s_add_u32 s14, s94, 0x40200
	s_addc_u32 s15, s95, 0
	s_mov_b32 s3, 1
	s_mov_b64 s[18:19], 0
	v_mov_b32_e32 v0, 0
	s_branch .LBB0_1039

; __device__ __forceinline__ unsigned xb_ld(unsigned* p)              { return __hip_atomic_load(p, __ATOMIC_RELAXED, __HIP_MEMORY_SCOPE_AGENT); }
; #define XB_SPIN(cond, bar) do { unsigned _sp = 0; while (cond) { __builtin_amdgcn_s_sleep(1); \
;     if ((++_sp & 255u) == 0u) { if (xb_ld(&(bar)[XB_TMO])) break; if (_sp > XB_SPIN_CAP) { atomicAdd(&(bar)[XB_TMO], 1u); break; } } } } while (0)
; __device__ __forceinline__ void xcd_barrier(const XcdBarrier& b) {
;     ...
;             XB_SPIN(xb_ld(&bar[XB_XGEN(b.x)]) == gen, bar);
.LBB0_1041:
	global_load_dword v2, v0, s[16:17] sc1
	s_add_i32 s3, s3, 1
	s_mov_b64 s[22:23], -1
	s_waitcnt vmcnt(0)
	v_cmp_ge_u32_e32 vcc, v2, v1
	s_orn2_b64 s[12:13], vcc, exec
	s_branch .LBB0_1038

; __device__ __forceinline__ unsigned xb_ld(unsigned* p)              { return __hip_atomic_load(p, __ATOMIC_RELAXED, __HIP_MEMORY_SCOPE_AGENT); }
; __device__ __forceinline__ unsigned xb_add(unsigned* p, unsigned v) { return __hip_atomic_fetch_add(p, v, __ATOMIC_RELAXED, __HIP_MEMORY_SCOPE_AGENT); }
; #define XB_SPIN(cond, bar) do { unsigned _sp = 0; while (cond) { __builtin_amdgcn_s_sleep(1); \
;     if ((++_sp & 255u) == 0u) { if (xb_ld(&(bar)[XB_TMO])) break; if (_sp > XB_SPIN_CAP) { atomicAdd(&(bar)[XB_TMO], 1u); break; } } } } while (0)
; __device__ __forceinline__ void xcd_barrier(const XcdBarrier& b) {
;     ...
;             const unsigned og = xb_add(&bar[XB_TOP], 1u);
;             const unsigned tg = og / nx;
;             if (og + 1u == (tg + 1u) * nx) xb_add(&bar[XB_TOPGEN], 1u);
;             else XB_SPIN(xb_ld(&bar[XB_TOPGEN]) == tg, bar);
.LBB0_1052:
	s_or_b64 exec, exec, s[8:9]
	v_cvt_f32_u32_e32 v3, v0
	s_waitcnt vmcnt(0)
	v_readfirstlane_b32 s3, v2
	s_add_u32 s8, s94, 0x43500
	s_addc_u32 s9, s95, 0
	v_rcp_iflag_f32_e32 v3, v3
	v_add_u32_e32 v1, s3, v1
	v_add_u32_e32 v4, 1, v1
	s_mov_b64 s[12:13], -1
	v_mul_f32_e32 v2, 0x4f7ffffe, v3
	v_cvt_u32_f32_e32 v2, v2
	v_sub_u32_e32 v3, 0, v0
	v_mul_lo_u32 v3, v3, v2
	v_mul_hi_u32 v3, v2, v3
	v_add_u32_e32 v2, v2, v3
	v_mul_hi_u32 v2, v1, v2
	v_mul_lo_u32 v3, v2, v0
	v_sub_u32_e32 v1, v1, v3
	v_add_u32_e32 v5, 1, v2
	v_cmp_ge_u32_e32 vcc, v1, v0
	v_sub_u32_e32 v3, v1, v0
	s_nop 0
	v_cndmask_b32_e32 v2, v2, v5, vcc
	v_cndmask_b32_e32 v1, v1, v3, vcc
	v_add_u32_e32 v3, 1, v2
	v_cmp_ge_u32_e32 vcc, v1, v0
	s_nop 1
	v_cndmask_b32_e32 v2, v2, v3, vcc
	v_mul_lo_u32 v1, v0, v2
	v_add_u32_e32 v0, v1, v0
	v_mov_b32_e32 v30, v0
	v_cmp_ne_u32_e32 vcc, v4, v0
	v_mov_b64_e32 v[0:1], s[8:9]
	s_and_saveexec_b64 s[6:7], vcc
	s_cbranch_execz .LBB0_1064
	v_mov_b32_e32 v0, 0
	global_load_dword v1, v0, s[8:9] offset:-256 sc1
	s_mov_b64 s[12:13], 0
	s_waitcnt vmcnt(0)
	v_cmp_lt_u32_e32 vcc, v1, v30
	s_and_saveexec_b64 s[16:17], vcc
	s_cbranch_execz .LBB0_1063
	s_add_u32 s14, s94, 0x40200
	s_addc_u32 s15, s95, 0
	s_mov_b32 s3, 1
	s_mov_b64 s[18:19], 0
	s_branch .LBB0_1056

; __device__ __forceinline__ unsigned xb_ld(unsigned* p)              { return __hip_atomic_load(p, __ATOMIC_RELAXED, __HIP_MEMORY_SCOPE_AGENT); }
; #define XB_SPIN(cond, bar) do { unsigned _sp = 0; while (cond) { __builtin_amdgcn_s_sleep(1); \
;     if ((++_sp & 255u) == 0u) { if (xb_ld(&(bar)[XB_TMO])) break; if (_sp > XB_SPIN_CAP) { atomicAdd(&(bar)[XB_TMO], 1u); break; } } } } while (0)
; __device__ __forceinline__ void xcd_barrier(const XcdBarrier& b) {
;     ...
;             else XB_SPIN(xb_ld(&bar[XB_TOPGEN]) == tg, bar);
.LBB0_1058:
	global_load_dword v1, v0, s[8:9] offset:-256 sc1
	s_add_i32 s3, s3, 1
	s_mov_b64 s[12:13], -1
	s_waitcnt vmcnt(0)
	v_cmp_ge_u32_e32 vcc, v1, v30
	s_orn2_b64 s[24:25], vcc, exec
	s_branch .LBB0_1055
